# v16 + grid barrier flat release: non-last workgroups poll the top-level generation word directly, per-XCD generation bump removed
# speedup vs baseline: 1.0471x; 1.0014x over previous
.LBB0_108:
	s_or_b64 exec, exec, s[16:17]
	v_cvt_f32_u32_e32 v4, v2
	s_waitcnt vmcnt(0)
	v_readfirstlane_b32 s4, v3
	v_sub_u32_e32 v3, 0, v2
	v_rcp_iflag_f32_e32 v4, v4
	v_add_u32_e32 v5, s4, v1
	v_mul_f32_e32 v4, 0x4f7ffffe, v4
	v_cvt_u32_f32_e32 v4, v4
	v_mul_lo_u32 v1, v3, v4
	v_mul_hi_u32 v1, v4, v1
	v_add_u32_e32 v1, v4, v1
	v_mul_hi_u32 v1, v5, v1
	v_mul_lo_u32 v3, v1, v2
	v_sub_u32_e32 v3, v5, v3
	v_add_u32_e32 v4, 1, v1
	v_cmp_ge_u32_e32 vcc, v3, v2
	s_nop 1
	v_cndmask_b32_e32 v1, v1, v4, vcc
	v_sub_u32_e32 v4, v3, v2
	v_cndmask_b32_e32 v3, v3, v4, vcc
	v_add_u32_e32 v4, 1, v1
	v_cmp_ge_u32_e32 vcc, v3, v2
	v_add_u32_e32 v3, 1, v5
	s_nop 0
	v_cndmask_b32_e32 v1, v1, v4, vcc
	v_mul_lo_u32 v4, v2, v1
	v_add_u32_e32 v2, v4, v2
	v_cmp_ne_u32_e32 vcc, v3, v2
	s_and_saveexec_b64 s[4:5], vcc
	s_xor_b64 s[14:15], exec, s[4:5]
	s_cbranch_execz .LBB0_122
	s_waitcnt lgkmcnt(0)
	v_mov_b32_e32 v0, 0
	v_readlane_b32 s20, v237, 3
	v_readlane_b32 s21, v237, 4
	s_add_u32 s20, s20, 0x3500
	s_addc_u32 s21, s21, 0
	global_load_dword v0, v0, s[20:21] sc1
	s_waitcnt vmcnt(0)
	v_cmp_eq_u32_e32 vcc, v0, v1
	s_and_saveexec_b64 s[16:17], vcc
	s_cbranch_execz .LBB0_121
	s_add_u32 s18, s88, 0x4100200
	s_addc_u32 s19, s89, 0
	s_mov_b32 s4, 1
	s_mov_b64 s[22:23], 0
	v_mov_b32_e32 v0, 0
	s_branch .LBB0_112

.LBB0_139:
	s_or_b64 exec, exec, s[14:15]
	s_mov_b64 s[14:15], exec
	v_mbcnt_lo_u32_b32 v0, s14, 0
	v_mbcnt_hi_u32_b32 v0, s15, v0
	v_cmp_eq_u32_e32 vcc, 0, v0
	s_waitcnt vmcnt(0)
	buffer_inv sc1
	s_and_saveexec_b64 s[16:17], vcc
	s_cbranch_execz .LBB0_141
	s_bcnt1_i32_b64 s4, s[14:15]
	v_mov_b32_e32 v0, 0x2000
	v_mov_b32_e32 v1, s4
.LBB0_141:
	s_or_b64 exec, exec, s[16:17]
	s_waitcnt vmcnt(0)

.LBB0_194:
	s_or_b64 exec, exec, s[14:15]
	v_cvt_f32_u32_e32 v4, v2
	s_waitcnt vmcnt(0)
	v_readfirstlane_b32 s4, v3
	v_sub_u32_e32 v3, 0, v2
	v_rcp_iflag_f32_e32 v4, v4
	v_add_u32_e32 v5, s4, v1
	v_mul_f32_e32 v4, 0x4f7ffffe, v4
	v_cvt_u32_f32_e32 v4, v4
	v_mul_lo_u32 v1, v3, v4
	v_mul_hi_u32 v1, v4, v1
	v_add_u32_e32 v1, v4, v1
	v_mul_hi_u32 v1, v5, v1
	v_mul_lo_u32 v3, v1, v2
	v_sub_u32_e32 v3, v5, v3
	v_add_u32_e32 v4, 1, v1
	v_cmp_ge_u32_e32 vcc, v3, v2
	s_nop 1
	v_cndmask_b32_e32 v1, v1, v4, vcc
	v_sub_u32_e32 v4, v3, v2
	v_cndmask_b32_e32 v3, v3, v4, vcc
	v_add_u32_e32 v4, 1, v1
	v_cmp_ge_u32_e32 vcc, v3, v2
	v_add_u32_e32 v3, 1, v5
	s_nop 0
	v_cndmask_b32_e32 v1, v1, v4, vcc
	v_mul_lo_u32 v4, v2, v1
	v_add_u32_e32 v2, v4, v2
	v_cmp_ne_u32_e32 vcc, v3, v2
	s_and_saveexec_b64 s[4:5], vcc
	s_xor_b64 s[6:7], exec, s[4:5]
	s_cbranch_execz .LBB0_208
	s_waitcnt lgkmcnt(0)
	v_mov_b32_e32 v0, 0
	v_readlane_b32 s18, v237, 3
	v_readlane_b32 s19, v237, 4
	s_add_u32 s18, s18, 0x3500
	s_addc_u32 s19, s19, 0
	global_load_dword v0, v0, s[18:19] sc1
	s_waitcnt vmcnt(0)
	v_cmp_eq_u32_e32 vcc, v0, v1
	s_and_saveexec_b64 s[14:15], vcc
	s_cbranch_execz .LBB0_207
	s_add_u32 s16, s88, 0x4100200
	s_addc_u32 s17, s89, 0
	s_mov_b32 s4, 1
	s_mov_b64 s[20:21], 0
	v_mov_b32_e32 v0, 0
	s_branch .LBB0_198

.LBB0_225:
	s_or_b64 exec, exec, s[6:7]
	s_mov_b64 s[6:7], exec
	v_mbcnt_lo_u32_b32 v0, s6, 0
	v_mbcnt_hi_u32_b32 v0, s7, v0
	v_cmp_eq_u32_e32 vcc, 0, v0
	s_waitcnt vmcnt(0)
	buffer_inv sc1
	s_and_saveexec_b64 s[14:15], vcc
	s_cbranch_execz .LBB0_227
	s_bcnt1_i32_b64 s4, s[6:7]
	v_mov_b32_e32 v0, 0x2000
	v_mov_b32_e32 v1, s4
.LBB0_227:
	s_or_b64 exec, exec, s[14:15]
	s_waitcnt vmcnt(0)

.LBB0_300:
	s_or_b64 exec, exec, s[6:7]
	s_mov_b64 s[6:7], exec
	v_mbcnt_lo_u32_b32 v0, s6, 0
	v_mbcnt_hi_u32_b32 v0, s7, v0
	v_cmp_eq_u32_e32 vcc, 0, v0
	s_waitcnt vmcnt(0)
	buffer_inv sc1
	s_and_saveexec_b64 s[14:15], vcc
	s_cbranch_execz .LBB0_302
	s_bcnt1_i32_b64 s4, s[6:7]
	v_mov_b32_e32 v0, 0x2000
	v_mov_b32_e32 v1, s4
.LBB0_302:
	s_or_b64 exec, exec, s[14:15]
	s_waitcnt vmcnt(0)

.LBB0_353:
	s_or_b64 exec, exec, s[12:13]
	v_cvt_f32_u32_e32 v4, v2
	s_waitcnt vmcnt(0)
	v_readfirstlane_b32 s4, v3
	v_sub_u32_e32 v3, 0, v2
	v_rcp_iflag_f32_e32 v4, v4
	v_add_u32_e32 v5, s4, v1
	v_mul_f32_e32 v4, 0x4f7ffffe, v4
	v_cvt_u32_f32_e32 v4, v4
	v_mul_lo_u32 v1, v3, v4
	v_mul_hi_u32 v1, v4, v1
	v_add_u32_e32 v1, v4, v1
	v_mul_hi_u32 v1, v5, v1
	v_mul_lo_u32 v3, v1, v2
	v_sub_u32_e32 v3, v5, v3
	v_add_u32_e32 v4, 1, v1
	v_cmp_ge_u32_e32 vcc, v3, v2
	s_nop 1
	v_cndmask_b32_e32 v1, v1, v4, vcc
	v_sub_u32_e32 v4, v3, v2
	v_cndmask_b32_e32 v3, v3, v4, vcc
	v_add_u32_e32 v4, 1, v1
	v_cmp_ge_u32_e32 vcc, v3, v2
	v_add_u32_e32 v3, 1, v5
	s_nop 0
	v_cndmask_b32_e32 v1, v1, v4, vcc
	v_mul_lo_u32 v4, v2, v1
	v_add_u32_e32 v2, v4, v2
	v_cmp_ne_u32_e32 vcc, v3, v2
	s_and_saveexec_b64 s[4:5], vcc
	s_xor_b64 s[6:7], exec, s[4:5]
	s_cbranch_execz .LBB0_367
	s_waitcnt lgkmcnt(0)
	v_mov_b32_e32 v0, 0
	v_readlane_b32 s16, v237, 3
	v_readlane_b32 s17, v237, 4
	s_add_u32 s16, s16, 0x3500
	s_addc_u32 s17, s17, 0
	global_load_dword v0, v0, s[16:17] sc1
	s_waitcnt vmcnt(0)
	v_cmp_eq_u32_e32 vcc, v0, v1
	s_and_saveexec_b64 s[12:13], vcc
	s_cbranch_execz .LBB0_366
	s_add_u32 s14, s88, 0x4100200
	s_addc_u32 s15, s89, 0
	s_mov_b32 s4, 1
	s_mov_b64 s[18:19], 0
	v_mov_b32_e32 v0, 0
	s_branch .LBB0_357

.LBB0_384:
	s_or_b64 exec, exec, s[6:7]
	s_mov_b64 s[6:7], exec
	v_mbcnt_lo_u32_b32 v0, s6, 0
	v_mbcnt_hi_u32_b32 v0, s7, v0
	v_cmp_eq_u32_e32 vcc, 0, v0
	s_waitcnt vmcnt(0)
	buffer_inv sc1
	s_and_saveexec_b64 s[12:13], vcc
	s_cbranch_execz .LBB0_386
	s_bcnt1_i32_b64 s4, s[6:7]
	v_mov_b32_e32 v0, 0x2000
	v_mov_b32_e32 v1, s4
.LBB0_386:
	s_or_b64 exec, exec, s[12:13]
	s_waitcnt vmcnt(0)

.LBB0_432:
	s_or_b64 exec, exec, s[10:11]
	v_cvt_f32_u32_e32 v4, v2
	s_waitcnt vmcnt(0)
	v_readfirstlane_b32 s4, v3
	v_sub_u32_e32 v3, 0, v2
	v_rcp_iflag_f32_e32 v4, v4
	v_add_u32_e32 v5, s4, v1
	v_mul_f32_e32 v4, 0x4f7ffffe, v4
	v_cvt_u32_f32_e32 v4, v4
	v_mul_lo_u32 v1, v3, v4
	v_mul_hi_u32 v1, v4, v1
	v_add_u32_e32 v1, v4, v1
	v_mul_hi_u32 v1, v5, v1
	v_mul_lo_u32 v3, v1, v2
	v_sub_u32_e32 v3, v5, v3
	v_add_u32_e32 v4, 1, v1
	v_cmp_ge_u32_e32 vcc, v3, v2
	s_nop 1
	v_cndmask_b32_e32 v1, v1, v4, vcc
	v_sub_u32_e32 v4, v3, v2
	v_cndmask_b32_e32 v3, v3, v4, vcc
	v_add_u32_e32 v4, 1, v1
	v_cmp_ge_u32_e32 vcc, v3, v2
	v_add_u32_e32 v3, 1, v5
	s_nop 0
	v_cndmask_b32_e32 v1, v1, v4, vcc
	v_mul_lo_u32 v4, v2, v1
	v_add_u32_e32 v2, v4, v2
	v_cmp_ne_u32_e32 vcc, v3, v2
	s_and_saveexec_b64 s[4:5], vcc
	s_xor_b64 s[6:7], exec, s[4:5]
	s_cbranch_execz .LBB0_446
	s_waitcnt lgkmcnt(0)
	v_mov_b32_e32 v0, 0
	v_readlane_b32 s14, v237, 3
	v_readlane_b32 s15, v237, 4
	s_add_u32 s14, s14, 0x3500
	s_addc_u32 s15, s15, 0
	global_load_dword v0, v0, s[14:15] sc1
	s_waitcnt vmcnt(0)
	v_cmp_eq_u32_e32 vcc, v0, v1
	s_and_saveexec_b64 s[10:11], vcc
	s_cbranch_execz .LBB0_445
	s_add_u32 s12, s88, 0x4100200
	s_addc_u32 s13, s89, 0
	s_mov_b32 s4, 1
	s_mov_b64 s[16:17], 0
	v_mov_b32_e32 v0, 0
	s_branch .LBB0_436

.LBB0_463:
	s_or_b64 exec, exec, s[6:7]
	s_mov_b64 s[6:7], exec
	v_mbcnt_lo_u32_b32 v0, s6, 0
	v_mbcnt_hi_u32_b32 v0, s7, v0
	v_cmp_eq_u32_e32 vcc, 0, v0
	s_waitcnt vmcnt(0)
	buffer_inv sc1
	s_and_saveexec_b64 s[10:11], vcc
	s_cbranch_execz .LBB0_465
	s_bcnt1_i32_b64 s4, s[6:7]
	v_mov_b32_e32 v0, 0x2000
	v_mov_b32_e32 v1, s4
.LBB0_465:
	s_or_b64 exec, exec, s[10:11]
	s_waitcnt vmcnt(0)

.LBB0_511:
	s_or_b64 exec, exec, s[8:9]
	v_cvt_f32_u32_e32 v4, v2
	s_waitcnt vmcnt(0)
	v_readfirstlane_b32 s4, v3
	v_sub_u32_e32 v3, 0, v2
	v_rcp_iflag_f32_e32 v4, v4
	v_add_u32_e32 v5, s4, v1
	v_mul_f32_e32 v4, 0x4f7ffffe, v4
	v_cvt_u32_f32_e32 v4, v4
	v_mul_lo_u32 v1, v3, v4
	v_mul_hi_u32 v1, v4, v1
	v_add_u32_e32 v1, v4, v1
	v_mul_hi_u32 v1, v5, v1
	v_mul_lo_u32 v3, v1, v2
	v_sub_u32_e32 v3, v5, v3
	v_add_u32_e32 v4, 1, v1
	v_cmp_ge_u32_e32 vcc, v3, v2
	s_nop 1
	v_cndmask_b32_e32 v1, v1, v4, vcc
	v_sub_u32_e32 v4, v3, v2
	v_cndmask_b32_e32 v3, v3, v4, vcc
	v_add_u32_e32 v4, 1, v1
	v_cmp_ge_u32_e32 vcc, v3, v2
	v_add_u32_e32 v3, 1, v5
	s_nop 0
	v_cndmask_b32_e32 v1, v1, v4, vcc
	v_mul_lo_u32 v4, v2, v1
	v_add_u32_e32 v2, v4, v2
	v_cmp_ne_u32_e32 vcc, v3, v2
	s_and_saveexec_b64 s[4:5], vcc
	s_xor_b64 s[6:7], exec, s[4:5]
	s_cbranch_execz .LBB0_525
	s_waitcnt lgkmcnt(0)
	v_mov_b32_e32 v0, 0
	v_readlane_b32 s12, v237, 3
	v_readlane_b32 s13, v237, 4
	s_add_u32 s12, s12, 0x3500
	s_addc_u32 s13, s13, 0
	global_load_dword v0, v0, s[12:13] sc1
	s_waitcnt vmcnt(0)
	v_cmp_eq_u32_e32 vcc, v0, v1
	s_and_saveexec_b64 s[8:9], vcc
	s_cbranch_execz .LBB0_524
	s_add_u32 s10, s88, 0x4100200
	s_addc_u32 s11, s89, 0
	s_mov_b32 s4, 1
	s_mov_b64 s[14:15], 0
	v_mov_b32_e32 v0, 0
	s_branch .LBB0_515

.LBB0_542:
	s_or_b64 exec, exec, s[6:7]
	s_mov_b64 s[6:7], exec
	v_mbcnt_lo_u32_b32 v0, s6, 0
	v_mbcnt_hi_u32_b32 v0, s7, v0
	v_cmp_eq_u32_e32 vcc, 0, v0
	s_waitcnt vmcnt(0)
	buffer_inv sc1
	s_and_saveexec_b64 s[8:9], vcc
	s_cbranch_execz .LBB0_544
	s_bcnt1_i32_b64 s4, s[6:7]
	v_mov_b32_e32 v0, 0x2000
	v_mov_b32_e32 v1, s4
.LBB0_544:
	s_or_b64 exec, exec, s[8:9]
	s_waitcnt vmcnt(0)

.LBB0_643:
	s_or_b64 exec, exec, s[6:7]
	s_mov_b64 s[6:7], exec
	v_mbcnt_lo_u32_b32 v0, s6, 0
	v_mbcnt_hi_u32_b32 v0, s7, v0
	v_cmp_eq_u32_e32 vcc, 0, v0
	s_waitcnt vmcnt(0)
	buffer_inv sc1
	s_and_saveexec_b64 s[8:9], vcc
	s_cbranch_execz .LBB0_645
	s_bcnt1_i32_b64 s4, s[6:7]
	v_mov_b32_e32 v0, 0x2000
	v_mov_b32_e32 v1, s4
.LBB0_645:
	s_or_b64 exec, exec, s[8:9]
	s_waitcnt vmcnt(0)

.LBB0_752:
	s_or_b64 exec, exec, s[6:7]
	v_cvt_f32_u32_e32 v4, v2
	s_waitcnt vmcnt(0)
	v_readfirstlane_b32 s4, v3
	v_sub_u32_e32 v3, 0, v2
	v_rcp_iflag_f32_e32 v4, v4
	v_add_u32_e32 v5, s4, v1
	v_mul_f32_e32 v4, 0x4f7ffffe, v4
	v_cvt_u32_f32_e32 v4, v4
	v_mul_lo_u32 v1, v3, v4
	v_mul_hi_u32 v1, v4, v1
	v_add_u32_e32 v1, v4, v1
	v_mul_hi_u32 v1, v5, v1
	v_mul_lo_u32 v3, v1, v2
	v_sub_u32_e32 v3, v5, v3
	v_add_u32_e32 v4, 1, v1
	v_cmp_ge_u32_e32 vcc, v3, v2
	s_nop 1
	v_cndmask_b32_e32 v1, v1, v4, vcc
	v_sub_u32_e32 v4, v3, v2
	v_cndmask_b32_e32 v3, v3, v4, vcc
	v_add_u32_e32 v4, 1, v1
	v_cmp_ge_u32_e32 vcc, v3, v2
	v_add_u32_e32 v3, 1, v5
	s_nop 0
	v_cndmask_b32_e32 v1, v1, v4, vcc
	v_mul_lo_u32 v4, v2, v1
	v_add_u32_e32 v2, v4, v2
	v_cmp_ne_u32_e32 vcc, v3, v2
	s_and_saveexec_b64 s[4:5], vcc
	s_xor_b64 s[4:5], exec, s[4:5]
	s_cbranch_execz .LBB0_766
	s_waitcnt lgkmcnt(0)
	v_mov_b32_e32 v0, 0
	v_readlane_b32 s10, v237, 3
	v_readlane_b32 s11, v237, 4
	s_add_u32 s10, s10, 0x3500
	s_addc_u32 s11, s11, 0
	global_load_dword v0, v0, s[10:11] sc1
	s_waitcnt vmcnt(0)
	v_cmp_eq_u32_e32 vcc, v0, v1
	s_and_saveexec_b64 s[6:7], vcc
	s_cbranch_execz .LBB0_765
	v_readlane_b32 s12, v237, 56
	v_readlane_b32 s13, v237, 57
	s_add_u32 s8, s12, 0x4100200
	v_readlane_b32 s14, v237, 58
	v_readlane_b32 s15, v237, 59
	s_addc_u32 s9, s13, 0
	s_mov_b32 s16, 1
	s_mov_b64 s[12:13], 0
	v_mov_b32_e32 v0, 0
	s_branch .LBB0_756

.LBB0_783:
	s_or_b64 exec, exec, s[4:5]
	s_mov_b64 s[4:5], exec
	v_mbcnt_lo_u32_b32 v0, s4, 0
	v_mbcnt_hi_u32_b32 v0, s5, v0
	v_cmp_eq_u32_e32 vcc, 0, v0
	s_waitcnt vmcnt(0)
	buffer_inv sc1
	s_and_saveexec_b64 s[6:7], vcc
	s_cbranch_execz .LBB0_785
	s_bcnt1_i32_b64 s4, s[4:5]
	v_mov_b32_e32 v0, 0x2000
	v_mov_b32_e32 v1, s4
.LBB0_785:
	s_or_b64 exec, exec, s[6:7]
	s_waitcnt vmcnt(0)

.LBB0_922:
	s_or_b64 exec, exec, s[4:5]
	s_mov_b64 s[4:5], exec
	v_mbcnt_lo_u32_b32 v0, s4, 0
	v_mbcnt_hi_u32_b32 v0, s5, v0
	v_cmp_eq_u32_e32 vcc, 0, v0
	s_waitcnt vmcnt(0)
	buffer_inv sc1
	s_and_saveexec_b64 s[6:7], vcc
	s_cbranch_execz .LBB0_924
	s_bcnt1_i32_b64 s4, s[4:5]
	v_mov_b32_e32 v0, 0x2000
	v_mov_b32_e32 v1, s4
.LBB0_924:
	s_or_b64 exec, exec, s[6:7]
	s_waitcnt vmcnt(0)

.LBB0_977:
	s_or_b64 exec, exec, s[4:5]
	s_mov_b64 s[4:5], exec
	v_mbcnt_lo_u32_b32 v0, s4, 0
	v_mbcnt_hi_u32_b32 v0, s5, v0
	v_cmp_eq_u32_e32 vcc, 0, v0
	s_waitcnt vmcnt(0)
	buffer_inv sc1
	s_and_saveexec_b64 s[6:7], vcc
	s_cbranch_execz .LBB0_979
	s_bcnt1_i32_b64 s4, s[4:5]
	v_mov_b32_e32 v0, 0x2000
	v_mov_b32_e32 v1, s4
.LBB0_979:
	s_or_b64 exec, exec, s[6:7]
	s_waitcnt vmcnt(0)

.LBB0_1033:
	s_or_b64 exec, exec, s[8:9]
	v_cvt_f32_u32_e32 v4, v2
	s_waitcnt vmcnt(0)
	v_readfirstlane_b32 s6, v3
	v_sub_u32_e32 v3, 0, v2
	v_rcp_iflag_f32_e32 v4, v4
	v_add_u32_e32 v5, s6, v1
	v_mul_f32_e32 v4, 0x4f7ffffe, v4
	v_cvt_u32_f32_e32 v4, v4
	v_mul_lo_u32 v1, v3, v4
	v_mul_hi_u32 v1, v4, v1
	v_add_u32_e32 v1, v4, v1
	v_mul_hi_u32 v1, v5, v1
	v_mul_lo_u32 v3, v1, v2
	v_sub_u32_e32 v3, v5, v3
	v_add_u32_e32 v4, 1, v1
	v_cmp_ge_u32_e32 vcc, v3, v2
	s_nop 1
	v_cndmask_b32_e32 v1, v1, v4, vcc
	v_sub_u32_e32 v4, v3, v2
	v_cndmask_b32_e32 v3, v3, v4, vcc
	v_add_u32_e32 v4, 1, v1
	v_cmp_ge_u32_e32 vcc, v3, v2
	v_add_u32_e32 v3, 1, v5
	s_nop 0
	v_cndmask_b32_e32 v1, v1, v4, vcc
	v_mul_lo_u32 v4, v2, v1
	v_add_u32_e32 v2, v4, v2
	v_cmp_ne_u32_e32 vcc, v3, v2
	s_and_saveexec_b64 s[6:7], vcc
	s_xor_b64 s[6:7], exec, s[6:7]
	s_cbranch_execz .LBB0_1047
	s_waitcnt lgkmcnt(0)
	v_mov_b32_e32 v0, 0
	v_readlane_b32 s12, v237, 3
	v_readlane_b32 s13, v237, 4
	s_add_u32 s12, s12, 0x3500
	s_addc_u32 s13, s13, 0
	global_load_dword v0, v0, s[12:13] sc1
	s_waitcnt vmcnt(0)
	v_cmp_eq_u32_e32 vcc, v0, v1
	s_and_saveexec_b64 s[8:9], vcc
	s_cbranch_execz .LBB0_1046
	v_readlane_b32 s16, v237, 56
	v_readlane_b32 s17, v237, 57
	s_add_u32 s10, s16, 0x4100200
	v_readlane_b32 s18, v237, 58
	v_readlane_b32 s19, v237, 59
	s_addc_u32 s11, s17, 0
	s_mov_b32 s16, 1
	s_mov_b64 s[14:15], 0
	v_mov_b32_e32 v0, 0
	s_branch .LBB0_1037

.LBB0_1064:
	s_or_b64 exec, exec, s[6:7]
	s_mov_b64 s[6:7], exec
	v_mbcnt_lo_u32_b32 v0, s6, 0
	v_mbcnt_hi_u32_b32 v0, s7, v0
	v_cmp_eq_u32_e32 vcc, 0, v0
	s_waitcnt vmcnt(0)
	buffer_inv sc1
	s_and_saveexec_b64 s[8:9], vcc
	s_cbranch_execz .LBB0_1066
	s_bcnt1_i32_b64 s6, s[6:7]
	v_mov_b32_e32 v0, 0x2000
	v_mov_b32_e32 v1, s6
.LBB0_1066:
	s_or_b64 exec, exec, s[8:9]
	s_waitcnt vmcnt(0)

.LBB0_1127:
	s_or_b64 exec, exec, s[6:7]
	s_mov_b64 s[6:7], exec
	v_mbcnt_lo_u32_b32 v0, s6, 0
	v_mbcnt_hi_u32_b32 v0, s7, v0
	v_cmp_eq_u32_e32 vcc, 0, v0
	s_waitcnt vmcnt(0)
	buffer_inv sc1
	s_and_saveexec_b64 s[8:9], vcc
	s_cbranch_execz .LBB0_1129
	s_bcnt1_i32_b64 s6, s[6:7]
	v_mov_b32_e32 v0, 0x2000
	v_mov_b32_e32 v1, s6
.LBB0_1129:
	s_or_b64 exec, exec, s[8:9]
	s_waitcnt vmcnt(0)

.LBB0_1445:
	s_or_b64 exec, exec, s[6:7]
	s_mov_b64 s[6:7], exec
	v_mbcnt_lo_u32_b32 v0, s6, 0
	v_mbcnt_hi_u32_b32 v0, s7, v0
	v_cmp_eq_u32_e32 vcc, 0, v0
	s_waitcnt vmcnt(0)
	buffer_inv sc1
	s_and_saveexec_b64 s[8:9], vcc
	s_cbranch_execz .LBB0_1447
	s_bcnt1_i32_b64 s6, s[6:7]
	v_mov_b32_e32 v0, 0x2000
	v_mov_b32_e32 v1, s6
.LBB0_1447:
	s_or_b64 exec, exec, s[8:9]
	s_waitcnt vmcnt(0)

.LBB0_1495:
	s_or_b64 exec, exec, s[10:11]
	v_cvt_f32_u32_e32 v4, v2
	s_waitcnt vmcnt(0)
	v_readfirstlane_b32 s6, v3
	v_sub_u32_e32 v3, 0, v2
	v_rcp_iflag_f32_e32 v4, v4
	v_add_u32_e32 v5, s6, v1
	v_mul_f32_e32 v4, 0x4f7ffffe, v4
	v_cvt_u32_f32_e32 v4, v4
	v_mul_lo_u32 v1, v3, v4
	v_mul_hi_u32 v1, v4, v1
	v_add_u32_e32 v1, v4, v1
	v_mul_hi_u32 v1, v5, v1
	v_mul_lo_u32 v3, v1, v2
	v_sub_u32_e32 v3, v5, v3
	v_add_u32_e32 v4, 1, v1
	v_cmp_ge_u32_e32 vcc, v3, v2
	s_nop 1
	v_cndmask_b32_e32 v1, v1, v4, vcc
	v_sub_u32_e32 v4, v3, v2
	v_cndmask_b32_e32 v3, v3, v4, vcc
	v_add_u32_e32 v4, 1, v1
	v_cmp_ge_u32_e32 vcc, v3, v2
	v_add_u32_e32 v3, 1, v5
	s_nop 0
	v_cndmask_b32_e32 v1, v1, v4, vcc
	v_mul_lo_u32 v4, v2, v1
	v_add_u32_e32 v2, v4, v2
	v_cmp_ne_u32_e32 vcc, v3, v2
	s_and_saveexec_b64 s[6:7], vcc
	s_xor_b64 s[6:7], exec, s[6:7]
	s_cbranch_execz .LBB0_1509
	s_waitcnt lgkmcnt(0)
	v_mov_b32_e32 v0, 0
	v_readlane_b32 s14, v237, 3
	v_readlane_b32 s15, v237, 4
	s_add_u32 s14, s14, 0x3500
	s_addc_u32 s15, s15, 0
	global_load_dword v0, v0, s[14:15] sc1
	s_waitcnt vmcnt(0)
	v_cmp_eq_u32_e32 vcc, v0, v1
	s_and_saveexec_b64 s[10:11], vcc
	s_cbranch_execz .LBB0_1508
	v_readlane_b32 s16, v237, 56
	v_readlane_b32 s17, v237, 57
	v_readlane_b32 s18, v237, 58
	v_readlane_b32 s19, v237, 59
	s_add_u32 s12, s16, 0x4100200
	s_addc_u32 s13, s17, 0
	s_mov_b32 s16, 1
	s_mov_b64 s[18:19], 0
	v_mov_b32_e32 v0, 0
	s_branch .LBB0_1499

.LBB0_1526:
	s_or_b64 exec, exec, s[6:7]
	s_mov_b64 s[6:7], exec
	v_mbcnt_lo_u32_b32 v0, s6, 0
	v_mbcnt_hi_u32_b32 v0, s7, v0
	v_cmp_eq_u32_e32 vcc, 0, v0
	s_waitcnt vmcnt(0)
	buffer_inv sc1
	s_and_saveexec_b64 s[10:11], vcc
	s_cbranch_execz .LBB0_1528
	s_bcnt1_i32_b64 s6, s[6:7]
	v_mov_b32_e32 v0, 0x2000
	v_mov_b32_e32 v1, s6
.LBB0_1528:
	s_or_b64 exec, exec, s[10:11]
	s_waitcnt vmcnt(0)

.LBB0_1587:
	s_or_b64 exec, exec, s[4:5]
	s_mov_b64 s[4:5], exec
	v_mbcnt_lo_u32_b32 v0, s4, 0
	v_mbcnt_hi_u32_b32 v0, s5, v0
	v_cmp_eq_u32_e32 vcc, 0, v0
	s_waitcnt vmcnt(0)
	buffer_inv sc1
	s_and_saveexec_b64 s[6:7], vcc
	s_cbranch_execz .LBB0_1589
	s_bcnt1_i32_b64 s4, s[4:5]
	v_mov_b32_e32 v0, 0x2000
	v_mov_b32_e32 v1, s4
.LBB0_1589:
	s_or_b64 exec, exec, s[6:7]
	s_waitcnt vmcnt(0)

.LBB0_1666:
	s_or_b64 exec, exec, s[4:5]
	s_mov_b64 s[4:5], exec
	v_mbcnt_lo_u32_b32 v0, s4, 0
	v_mbcnt_hi_u32_b32 v0, s5, v0
	v_cmp_eq_u32_e32 vcc, 0, v0
	s_waitcnt vmcnt(0)
	buffer_inv sc1
	s_and_saveexec_b64 s[6:7], vcc
	s_cbranch_execz .LBB0_1668
	s_bcnt1_i32_b64 s4, s[4:5]
	v_mov_b32_e32 v0, 0x2000
	v_mov_b32_e32 v1, s4
.LBB0_1668:
	s_or_b64 exec, exec, s[6:7]
	s_waitcnt vmcnt(0)

.LBB0_1767:
	s_or_b64 exec, exec, s[4:5]
	s_mov_b64 s[4:5], exec
	v_mbcnt_lo_u32_b32 v0, s4, 0
	v_mbcnt_hi_u32_b32 v0, s5, v0
	v_cmp_eq_u32_e32 vcc, 0, v0
	s_waitcnt vmcnt(0)
	buffer_inv sc1
	s_and_saveexec_b64 s[6:7], vcc
	s_cbranch_execz .LBB0_1769
	s_bcnt1_i32_b64 s4, s[4:5]
	v_mov_b32_e32 v0, 0x2000
	v_mov_b32_e32 v1, s4
.LBB0_1769:
	s_or_b64 exec, exec, s[6:7]
	s_waitcnt vmcnt(0)

.LBB0_1876:
	s_or_b64 exec, exec, s[8:9]
	v_cvt_f32_u32_e32 v4, v2
	s_waitcnt vmcnt(0)
	v_readfirstlane_b32 s6, v3
	v_sub_u32_e32 v3, 0, v2
	v_rcp_iflag_f32_e32 v4, v4
	v_add_u32_e32 v5, s6, v1
	v_mul_f32_e32 v4, 0x4f7ffffe, v4
	v_cvt_u32_f32_e32 v4, v4
	v_mul_lo_u32 v1, v3, v4
	v_mul_hi_u32 v1, v4, v1
	v_add_u32_e32 v1, v4, v1
	v_mul_hi_u32 v1, v5, v1
	v_mul_lo_u32 v3, v1, v2
	v_sub_u32_e32 v3, v5, v3
	v_add_u32_e32 v4, 1, v1
	v_cmp_ge_u32_e32 vcc, v3, v2
	s_nop 1
	v_cndmask_b32_e32 v1, v1, v4, vcc
	v_sub_u32_e32 v4, v3, v2
	v_cndmask_b32_e32 v3, v3, v4, vcc
	v_add_u32_e32 v4, 1, v1
	v_cmp_ge_u32_e32 vcc, v3, v2
	v_add_u32_e32 v3, 1, v5
	s_nop 0
	v_cndmask_b32_e32 v1, v1, v4, vcc
	v_mul_lo_u32 v4, v2, v1
	v_add_u32_e32 v2, v4, v2
	v_cmp_ne_u32_e32 vcc, v3, v2
	s_and_saveexec_b64 s[6:7], vcc
	s_xor_b64 s[6:7], exec, s[6:7]
	s_cbranch_execz .LBB0_1890
	s_waitcnt lgkmcnt(0)
	v_mov_b32_e32 v0, 0
	v_readlane_b32 s12, v237, 3
	v_readlane_b32 s13, v237, 4
	s_add_u32 s12, s12, 0x3500
	s_addc_u32 s13, s13, 0
	global_load_dword v0, v0, s[12:13] sc1
	s_waitcnt vmcnt(0)
	v_cmp_eq_u32_e32 vcc, v0, v1
	s_and_saveexec_b64 s[8:9], vcc
	s_cbranch_execz .LBB0_1889
	v_readlane_b32 s16, v237, 56
	v_readlane_b32 s17, v237, 57
	s_add_u32 s10, s16, 0x4100200
	s_addc_u32 s11, s17, 0
	s_mov_b32 s24, 1
	s_mov_b64 s[14:15], 0
	v_mov_b32_e32 v0, 0
	v_readlane_b32 s18, v237, 58
	v_readlane_b32 s19, v237, 59
	s_branch .LBB0_1880

.LBB0_1907:
	s_or_b64 exec, exec, s[6:7]
	s_mov_b64 s[6:7], exec
	v_mbcnt_lo_u32_b32 v0, s6, 0
	v_mbcnt_hi_u32_b32 v0, s7, v0
	v_cmp_eq_u32_e32 vcc, 0, v0
	s_waitcnt vmcnt(0)
	buffer_inv sc1
	s_and_saveexec_b64 s[8:9], vcc
	s_cbranch_execz .LBB0_1909
	s_bcnt1_i32_b64 s6, s[6:7]
	v_mov_b32_e32 v0, 0x2000
	v_mov_b32_e32 v1, s6
.LBB0_1909:
	s_or_b64 exec, exec, s[8:9]
	s_waitcnt vmcnt(0)

.LBB0_2015:
	s_or_b64 exec, exec, s[6:7]
	v_cvt_f32_u32_e32 v4, v2
	s_waitcnt vmcnt(0)
	v_readfirstlane_b32 s4, v3
	v_sub_u32_e32 v3, 0, v2
	v_rcp_iflag_f32_e32 v4, v4
	v_add_u32_e32 v5, s4, v1
	v_mul_f32_e32 v4, 0x4f7ffffe, v4
	v_cvt_u32_f32_e32 v4, v4
	v_mul_lo_u32 v1, v3, v4
	v_mul_hi_u32 v1, v4, v1
	v_add_u32_e32 v1, v4, v1
	v_mul_hi_u32 v1, v5, v1
	v_mul_lo_u32 v3, v1, v2
	v_sub_u32_e32 v3, v5, v3
	v_add_u32_e32 v4, 1, v1
	v_cmp_ge_u32_e32 vcc, v3, v2
	s_nop 1
	v_cndmask_b32_e32 v1, v1, v4, vcc
	v_sub_u32_e32 v4, v3, v2
	v_cndmask_b32_e32 v3, v3, v4, vcc
	v_add_u32_e32 v4, 1, v1
	v_cmp_ge_u32_e32 vcc, v3, v2
	v_add_u32_e32 v3, 1, v5
	s_nop 0
	v_cndmask_b32_e32 v1, v1, v4, vcc
	v_mul_lo_u32 v4, v2, v1
	v_add_u32_e32 v2, v4, v2
	v_cmp_ne_u32_e32 vcc, v3, v2
	s_and_saveexec_b64 s[4:5], vcc
	s_xor_b64 s[4:5], exec, s[4:5]
	s_cbranch_execz .LBB0_2029
	s_waitcnt lgkmcnt(0)
	v_mov_b32_e32 v0, 0
	v_readlane_b32 s10, v237, 3
	v_readlane_b32 s11, v237, 4
	s_add_u32 s10, s10, 0x3500
	s_addc_u32 s11, s11, 0
	global_load_dword v0, v0, s[10:11] sc1
	s_waitcnt vmcnt(0)
	v_cmp_eq_u32_e32 vcc, v0, v1
	s_and_saveexec_b64 s[6:7], vcc
	s_cbranch_execz .LBB0_2028
	s_add_u32 s8, s52, 0x4100200
	s_addc_u32 s9, s53, 0
	s_mov_b32 s22, 1
	s_mov_b64 s[12:13], 0
	v_mov_b32_e32 v0, 0
	s_branch .LBB0_2019

.LBB0_2046:
	s_or_b64 exec, exec, s[4:5]
	s_mov_b64 s[4:5], exec
	v_mbcnt_lo_u32_b32 v0, s4, 0
	v_mbcnt_hi_u32_b32 v0, s5, v0
	v_cmp_eq_u32_e32 vcc, 0, v0
	s_waitcnt vmcnt(0)
	buffer_inv sc1
	s_and_saveexec_b64 s[6:7], vcc
	s_cbranch_execz .LBB0_2048
	s_bcnt1_i32_b64 s4, s[4:5]
	v_mov_b32_e32 v0, 0x2000
	v_mov_b32_e32 v1, s4
.LBB0_2048:
	s_or_b64 exec, exec, s[6:7]
	s_waitcnt vmcnt(0)
